# scan pass 1: redundant first workgroup barrier of the sub-tile loop removed (RAWU readers finish before barrier 3 of the previous sub-tile)
# baseline (speedup 1.0000x reference)
.LBB0_1849:
	s_waitcnt lgkmcnt(0)
	s_and_saveexec_b64 s[0:1], s[40:41]
	s_cbranch_execz .LBB0_1857
	v_add_u32_e32 v50, 0, v123
	ds_write_b128 v50, v[34:37]
	s_or_b64 exec, exec, s[0:1]
	s_and_saveexec_b64 s[0:1], s[42:43]
	s_cbranch_execnz .LBB0_1858
